# phase-4 kv-up K(nope) tiles stored via wave-private LDS transpose (8 row-contiguous dwordx4 per wave instead of 64 short stores)
# speedup vs baseline: 1.0057x; 1.0031x over previous
.LBB0_1675:
	s_andn2_b64 vcc, exec, s[0:1]
	s_cbranch_vccnz .LBB0_1708
	s_and_b32 s0, s27, 0x7f80
	s_addk_i32 s0, 0xd000
	s_mov_b32 s1, s77
	v_mov_b32_e32 v49, v186
	s_and_b32 s30, s29, 7
	s_lshl_b64 s[6:7], s[0:1], 9
	s_add_u32 s6, s18, s6
	v_lshlrev_b32_e32 v16, 4, v49
	v_ashrrev_i32_e32 v50, 3, v49
	v_and_b32_e32 v48, 0x70, v16
	s_addc_u32 s7, s19, s7
	v_lshl_or_b32 v160, v50, 9, v48
	s_waitcnt vmcnt(63) expcnt(7) lgkmcnt(15)
	s_barrier
	global_load_dwordx4 v[16:19], v160, s[6:7]
	s_lshl_b32 s1, s30, 16
	s_add_u32 s12, s22, s1
	s_addc_u32 s13, s23, 0
	v_add_u32_e32 v188, 0x4000, v160
	v_add_u32_e32 v189, 0x8000, v160
	v_add_u32_e32 v192, 0xc000, v160
	global_load_dwordx4 v[20:23], v188, s[6:7]
	global_load_dwordx4 v[24:27], v189, s[6:7]
	global_load_dwordx4 v[28:31], v192, s[6:7]
	global_load_dwordx4 v[32:35], v160, s[12:13]
	global_load_dwordx4 v[36:39], v188, s[12:13]
	global_load_dwordx4 v[40:43], v189, s[12:13]
	global_load_dwordx4 v[44:47], v192, s[12:13]
	v_mad_u64_u32 v[158:159], s[34:35], v50, s43, v[48:49]
	s_cmp_gt_u32 s30, 3
	s_waitcnt vmcnt(7)
	ds_write_b128 v158, v[16:19]
	v_lshrrev_b32_e32 v18, 1, v49
	v_and_b32_e32 v17, 0x5f, v49
	v_and_b32_e32 v16, 16, v18
	v_mad_u32_u24 v159, v17, s43, v16
	v_and_b32_e32 v17, 31, v49
	v_and_or_b32 v17, v18, s44, v17
	v_mad_u64_u32 v[156:157], s[34:35], v17, s43, v[16:17]
	s_waitcnt vmcnt(6)
	ds_write_b128 v158, v[20:23] offset:4608
	s_waitcnt vmcnt(5)
	ds_write_b128 v158, v[24:27] offset:9216
	s_waitcnt vmcnt(4)
	ds_write_b128 v158, v[28:31] offset:13824
	s_waitcnt vmcnt(3)
	ds_write_b128 v158, v[32:35] offset:36864
	s_waitcnt vmcnt(2)
	ds_write_b128 v158, v[36:39] offset:41472
	s_waitcnt vmcnt(1)
	ds_write_b128 v158, v[40:43] offset:46080
	s_waitcnt vmcnt(0)
	ds_write_b128 v158, v[44:47] offset:50688
	global_load_dwordx4 v[128:131], v160, s[6:7] offset:128
	global_load_dwordx4 v[132:135], v188, s[6:7] offset:128
	global_load_dwordx4 v[136:139], v189, s[6:7] offset:128
	global_load_dwordx4 v[140:143], v192, s[6:7] offset:128
	global_load_dwordx4 v[80:83], v160, s[12:13] offset:128
	global_load_dwordx4 v[84:87], v188, s[12:13] offset:128
	global_load_dwordx4 v[88:91], v189, s[12:13] offset:128
	global_load_dwordx4 v[92:95], v192, s[12:13] offset:128
	s_waitcnt lgkmcnt(0)
	s_barrier
	ds_read_b128 v[16:19], v156
	ds_read_b128 v[100:103], v159 offset:41472
	ds_read_b128 v[96:99], v156 offset:4608
	ds_read_b128 v[220:223], v156 offset:32
	s_waitcnt lgkmcnt(2)
	v_mfma_f32_32x32x16_bf16 v[64:79], v[16:19], v[100:103], v[0:15]
	ds_read_b128 v[32:35], v159 offset:36864
	ds_read_b128 v[224:227], v156 offset:4640
	ds_read_b128 v[228:231], v159 offset:36896
	ds_read_b128 v[232:235], v159 offset:41504
	v_add_u32_e32 v157, 0xd800, v158
	s_waitcnt lgkmcnt(3)
	v_mfma_f32_32x32x16_bf16 v[48:63], v[16:19], v[32:35], v[0:15]
	v_mfma_f32_32x32x16_bf16 v[16:31], v[96:99], v[32:35], v[0:15]
	v_mfma_f32_32x32x16_bf16 v[32:47], v[96:99], v[100:103], v[0:15]
	s_waitcnt lgkmcnt(1)
	v_mfma_f32_32x32x16_bf16 v[48:63], v[220:223], v[228:231], v[48:63]
	s_waitcnt lgkmcnt(0)
	v_mfma_f32_32x32x16_bf16 v[64:79], v[220:223], v[232:235], v[64:79]
	v_mfma_f32_32x32x16_bf16 v[16:31], v[224:227], v[228:231], v[16:31]
	v_mfma_f32_32x32x16_bf16 v[32:47], v[224:227], v[232:235], v[32:47]
	ds_read_b128 v[236:239], v156 offset:64
	ds_read_b128 v[240:243], v156 offset:4672
	ds_read_b128 v[244:247], v159 offset:36928
	ds_read_b128 v[200:203], v159 offset:41536
	s_waitcnt lgkmcnt(1)
	v_mfma_f32_32x32x16_bf16 v[48:63], v[236:239], v[244:247], v[48:63]
	s_waitcnt lgkmcnt(0)
	v_mfma_f32_32x32x16_bf16 v[64:79], v[236:239], v[200:203], v[64:79]
	v_mfma_f32_32x32x16_bf16 v[16:31], v[240:243], v[244:247], v[16:31]
	v_mfma_f32_32x32x16_bf16 v[32:47], v[240:243], v[200:203], v[32:47]
	global_load_dwordx4 v[112:115], v160, s[6:7] offset:256
	global_load_dwordx4 v[116:119], v188, s[6:7] offset:256
	global_load_dwordx4 v[120:123], v189, s[6:7] offset:256
	global_load_dwordx4 v[124:127], v192, s[6:7] offset:256
	global_load_dwordx4 v[96:99], v160, s[12:13] offset:256
	global_load_dwordx4 v[100:103], v188, s[12:13] offset:256
	global_load_dwordx4 v[104:107], v189, s[12:13] offset:256
	global_load_dwordx4 v[108:111], v192, s[12:13] offset:256
	s_waitcnt vmcnt(15)
	ds_write_b128 v158, v[128:131] offset:18432
	s_waitcnt vmcnt(14)
	ds_write_b128 v158, v[132:135] offset:23040
	s_waitcnt vmcnt(13)
	ds_write_b128 v158, v[136:139] offset:27648
	s_waitcnt vmcnt(12)
	ds_write_b128 v158, v[140:143] offset:32256
	ds_read_b128 v[128:131], v156 offset:96
	ds_read_b128 v[132:135], v156 offset:4704
	ds_read_b128 v[136:139], v159 offset:36960
	ds_read_b128 v[140:143], v159 offset:41568
	s_waitcnt vmcnt(11)
	ds_write_b128 v158, v[80:83] offset:55296
	s_waitcnt vmcnt(10)
	ds_write_b128 v158, v[84:87] offset:59904
	s_waitcnt vmcnt(9)
	ds_write_b128 v158, v[88:91] offset:64512
	s_waitcnt vmcnt(8)
	ds_write_b128 v157, v[92:95] offset:13824
	s_waitcnt lgkmcnt(5)
	v_mfma_f32_32x32x16_bf16 v[48:63], v[128:131], v[136:139], v[48:63]
	s_waitcnt lgkmcnt(0)
	s_barrier
	v_mfma_f32_32x32x16_bf16 v[64:79], v[128:131], v[140:143], v[64:79]
	v_mfma_f32_32x32x16_bf16 v[16:31], v[132:135], v[136:139], v[16:31]
	v_mfma_f32_32x32x16_bf16 v[32:47], v[132:135], v[140:143], v[32:47]
	ds_read_b128 v[80:83], v156 offset:23040
	ds_read_b128 v[88:91], v156 offset:18432
	ds_read_b128 v[84:87], v159 offset:59904
	ds_read_b128 v[92:95], v159 offset:55296
	ds_read_b128 v[128:131], v156 offset:18464
	ds_read_b128 v[132:135], v156 offset:23072
	ds_read_b128 v[136:139], v159 offset:55328
	ds_read_b128 v[140:143], v159 offset:59936
	s_waitcnt lgkmcnt(4)
	v_mfma_f32_32x32x16_bf16 v[48:63], v[88:91], v[92:95], v[48:63]
	v_mfma_f32_32x32x16_bf16 v[64:79], v[88:91], v[84:87], v[64:79]
	v_mfma_f32_32x32x16_bf16 v[16:31], v[80:83], v[92:95], v[16:31]
	v_mfma_f32_32x32x16_bf16 v[32:47], v[80:83], v[84:87], v[32:47]
	global_load_dwordx4 v[200:203], v160, s[6:7] offset:384
	global_load_dwordx4 v[220:223], v188, s[6:7] offset:384
	global_load_dwordx4 v[224:227], v189, s[6:7] offset:384
	global_load_dwordx4 v[228:231], v192, s[6:7] offset:384
	global_load_dwordx4 v[80:83], v160, s[12:13] offset:384
	global_load_dwordx4 v[84:87], v188, s[12:13] offset:384
	global_load_dwordx4 v[88:91], v189, s[12:13] offset:384
	global_load_dwordx4 v[92:95], v192, s[12:13] offset:384
	ds_read_b128 v[236:239], v156 offset:23104
	ds_read_b128 v[232:235], v156 offset:18496
	ds_read_b128 v[240:243], v159 offset:55360
	ds_read_b128 v[244:247], v159 offset:59968
	s_waitcnt vmcnt(15)
	ds_write_b128 v158, v[112:115]
	s_waitcnt vmcnt(14)
	ds_write_b128 v158, v[116:119] offset:4608
	s_waitcnt vmcnt(13)
	ds_write_b128 v158, v[120:123] offset:9216
	s_waitcnt vmcnt(12)
	ds_write_b128 v158, v[124:127] offset:13824
	s_waitcnt lgkmcnt(9)
	v_mfma_f32_32x32x16_bf16 v[16:31], v[132:135], v[136:139], v[16:31]
	s_cselect_b64 s[6:7], -1, 0
	s_and_b64 vcc, exec, s[6:7]
	s_waitcnt lgkmcnt(8)
	v_mfma_f32_32x32x16_bf16 v[32:47], v[132:135], v[140:143], v[32:47]
	ds_read_b128 v[116:119], v156 offset:23136
	ds_read_b128 v[112:115], v156 offset:18528
	ds_read_b128 v[120:123], v159 offset:55392
	ds_read_b128 v[124:127], v159 offset:60000
	s_waitcnt vmcnt(11)
	ds_write_b128 v158, v[96:99] offset:36864
	s_waitcnt vmcnt(10)
	ds_write_b128 v158, v[100:103] offset:41472
	s_waitcnt vmcnt(9)
	ds_write_b128 v158, v[104:107] offset:46080
	s_waitcnt vmcnt(8)
	ds_write_b128 v158, v[108:111] offset:50688
	s_waitcnt lgkmcnt(13)
	v_mfma_f32_32x32x16_bf16 v[16:31], v[236:239], v[240:243], v[16:31]
	s_waitcnt lgkmcnt(0)
	s_barrier
	v_mfma_f32_32x32x16_bf16 v[32:47], v[236:239], v[244:247], v[32:47]
	v_mfma_f32_32x32x16_bf16 v[16:31], v[116:119], v[120:123], v[16:31]
	v_mfma_f32_32x32x16_bf16 v[32:47], v[116:119], v[124:127], v[32:47]
	ds_read_b128 v[116:119], v156 offset:32
	v_mfma_f32_32x32x16_bf16 v[48:63], v[128:131], v[136:139], v[48:63]
	v_mfma_f32_32x32x16_bf16 v[64:79], v[128:131], v[140:143], v[64:79]
	v_mfma_f32_32x32x16_bf16 v[48:63], v[232:235], v[240:243], v[48:63]
	v_mfma_f32_32x32x16_bf16 v[64:79], v[232:235], v[244:247], v[64:79]
	v_mfma_f32_32x32x16_bf16 v[48:63], v[112:115], v[120:123], v[48:63]
	ds_read_b128 v[120:123], v159 offset:36928
	v_mfma_f32_32x32x16_bf16 v[64:79], v[112:115], v[124:127], v[64:79]
	ds_read_b128 v[112:115], v156
	ds_read_b128 v[96:99], v156 offset:4608
	ds_read_b128 v[100:103], v159 offset:41472
	ds_read_b128 v[124:127], v159 offset:41536
	s_waitcnt lgkmcnt(1)
	v_mfma_f32_32x32x16_bf16 v[64:79], v[112:115], v[100:103], v[64:79]
	v_mfma_f32_32x32x16_bf16 v[32:47], v[96:99], v[100:103], v[32:47]
	ds_read_b128 v[100:103], v156 offset:4640
	ds_read_b128 v[104:107], v159 offset:36864
	s_waitcnt lgkmcnt(0)
	v_mfma_f32_32x32x16_bf16 v[16:31], v[96:99], v[104:107], v[16:31]
	ds_read_b128 v[96:99], v159 offset:41504
	ds_read_b128 v[108:111], v159 offset:36896
	s_waitcnt lgkmcnt(1)
	v_mfma_f32_32x32x16_bf16 v[64:79], v[116:119], v[96:99], v[64:79]
	s_waitcnt lgkmcnt(0)
	v_mfma_f32_32x32x16_bf16 v[16:31], v[100:103], v[108:111], v[16:31]
	v_mfma_f32_32x32x16_bf16 v[32:47], v[100:103], v[96:99], v[32:47]
	v_mfma_f32_32x32x16_bf16 v[48:63], v[112:115], v[104:107], v[48:63]
	ds_read_b128 v[104:107], v156 offset:64
	ds_read_b128 v[112:115], v156 offset:4672
	s_waitcnt vmcnt(7)
	ds_write_b128 v158, v[200:203] offset:18432
	s_waitcnt vmcnt(6)
	ds_write_b128 v158, v[220:223] offset:23040
	s_waitcnt vmcnt(5)
	ds_write_b128 v158, v[224:227] offset:27648
	s_waitcnt vmcnt(4)
	ds_write_b128 v158, v[228:231] offset:32256
	ds_read_b128 v[96:99], v156 offset:96
	v_mfma_f32_32x32x16_bf16 v[48:63], v[116:119], v[108:111], v[48:63]
	ds_read_b128 v[100:103], v156 offset:4704
	ds_read_b128 v[108:111], v159 offset:36960
	ds_read_b128 v[116:119], v159 offset:41568
	s_waitcnt vmcnt(3)
	ds_write_b128 v158, v[80:83] offset:55296
	s_waitcnt vmcnt(2)
	ds_write_b128 v158, v[84:87] offset:59904
	s_waitcnt vmcnt(1)
	ds_write_b128 v158, v[88:91] offset:64512
	s_waitcnt vmcnt(0)
	ds_write_b128 v157, v[92:95] offset:13824
	s_waitcnt lgkmcnt(13)
	v_mfma_f32_32x32x16_bf16 v[48:63], v[104:107], v[120:123], v[48:63]
	s_waitcnt lgkmcnt(0)
	s_barrier
	ds_read_b128 v[80:83], v156 offset:23040
	ds_read_b128 v[88:91], v156 offset:18432
	ds_read_b128 v[84:87], v159 offset:59904
	ds_read_b128 v[92:95], v156 offset:18464
	v_mfma_f32_32x32x16_bf16 v[64:79], v[104:107], v[124:127], v[64:79]
	ds_read_b128 v[104:107], v159 offset:55328
	v_mfma_f32_32x32x16_bf16 v[16:31], v[112:115], v[120:123], v[16:31]
	ds_read_b128 v[120:123], v159 offset:55392
	v_mfma_f32_32x32x16_bf16 v[32:47], v[112:115], v[124:127], v[32:47]
	ds_read_b128 v[112:115], v156 offset:18528
	ds_read_b128 v[124:127], v159 offset:60000
	v_mfma_f32_32x32x16_bf16 v[48:63], v[96:99], v[108:111], v[48:63]
	v_mfma_f32_32x32x16_bf16 v[64:79], v[96:99], v[116:119], v[64:79]
	ds_read_b128 v[96:99], v156 offset:23072
	v_mfma_f32_32x32x16_bf16 v[16:31], v[100:103], v[108:111], v[16:31]
	ds_read_b128 v[108:111], v159 offset:59936
	v_mfma_f32_32x32x16_bf16 v[32:47], v[100:103], v[116:119], v[32:47]
	ds_read_b128 v[100:103], v159 offset:55296
	ds_read_b128 v[116:119], v156 offset:23136
	s_waitcnt lgkmcnt(1)
	v_mfma_f32_32x32x16_bf16 v[48:63], v[88:91], v[100:103], v[48:63]
	v_mfma_f32_32x32x16_bf16 v[64:79], v[88:91], v[84:87], v[64:79]
	ds_read_b128 v[88:91], v159 offset:55360
	v_mfma_f32_32x32x16_bf16 v[16:31], v[80:83], v[100:103], v[16:31]
	ds_read_b128 v[100:103], v159 offset:59968
	v_mfma_f32_32x32x16_bf16 v[32:47], v[80:83], v[84:87], v[32:47]
	ds_read_b128 v[80:83], v156 offset:18496
	ds_read_b128 v[84:87], v156 offset:23104
	s_waitcnt lgkmcnt(0)
	s_barrier
	v_mfma_f32_32x32x16_bf16 v[48:63], v[92:95], v[104:107], v[48:63]
	v_mfma_f32_32x32x16_bf16 v[64:79], v[92:95], v[108:111], v[64:79]
	v_mfma_f32_32x32x16_bf16 v[16:31], v[96:99], v[104:107], v[16:31]
	v_mfma_f32_32x32x16_bf16 v[32:47], v[96:99], v[108:111], v[32:47]
	v_mfma_f32_32x32x16_bf16 v[48:63], v[80:83], v[88:91], v[48:63]
	v_mfma_f32_32x32x16_bf16 v[64:79], v[80:83], v[100:103], v[64:79]
	v_add_u32_e32 v81, s0, v163
	s_movk_i32 s0, 0x1fc0
	v_lshl_or_b32 v80, s30, 1, v155
	v_mfma_f32_32x32x16_bf16 v[16:31], v[84:87], v[88:91], v[16:31]
	v_mfma_f32_32x32x16_bf16 v[32:47], v[84:87], v[100:103], v[32:47]
	v_and_or_b32 v86, v81, s0, v164
	v_ashrrev_i32_e32 v81, 10, v81
	v_and_b32_e32 v81, -8, v81
	v_add_u32_e32 v84, v81, v80
	v_add_u32_e32 v80, -8, v84
	v_ashrrev_i32_e32 v81, 31, v80
	v_lshlrev_b64 v[80:81], 20, v[80:81]
	v_mfma_f32_32x32x16_bf16 v[48:63], v[112:115], v[120:123], v[48:63]
	v_lshl_add_u64 v[82:83], v[148:149], 0, v[80:81]
	s_mov_b64 s[0:1], 0x80000
	v_lshl_add_u64 v[80:81], v[82:83], 0, s[0:1]
	s_mov_b64 s[0:1], -1
	v_mfma_f32_32x32x16_bf16 v[64:79], v[112:115], v[124:127], v[64:79]
	v_mfma_f32_32x32x16_bf16 v[16:31], v[116:119], v[120:123], v[16:31]
	v_mfma_f32_32x32x16_bf16 v[32:47], v[116:119], v[124:127], v[32:47]
	s_cmp_gt_u32 s30, 3
	s_cbranch_scc1 .Lp4kv_orig
	s_nop 15
	v_ashrrev_i32_e32 v85, 31, v84
	v_lshlrev_b64 v[84:85], 13, v[84:85]
	v_or_b32_e32 v87, v84, v86
	v_mad_u64_u32 v[88:89], s[32:33], v87, s38, v[150:151]
	v_mad_i32_i24 v89, v85, s38, v89
	s_nop 0
	v_readfirstlane_b32 s32, v88
	v_readfirstlane_b32 s33, v89
	v_readfirstlane_b32 s30, v186
	s_lshr_b32 s30, s30, 6
	s_mul_i32 s30, s30, 0x2400
	v_and_b32_e32 v90, 31, v186
	v_bfe_u32 v91, v186, 5, 1
	v_mul_u32_u24_e32 v91, 576, v91
	v_lshl_add_u32 v90, v90, 1, v91
	v_add_u32_e32 v90, s30, v90
	v_and_b32_e32 v92, 63, v186
	v_lshrrev_b32_e32 v93, 3, v92
	v_and_b32_e32 v92, 7, v92
	v_mul_u32_u24_e32 v94, 144, v93
	v_lshl_add_u32 v94, v92, 4, v94
	v_add_u32_e32 v94, s30, v94
	v_mul_u32_u24_e32 v95, 192, v93
	v_lshl_add_u32 v95, v92, 4, v95
	v_cvt_pk_bf16_f32 v96, v48, v49
	ds_write_b16 v90, v96
	ds_write_b16_d16_hi v90, v96 offset:144
	v_cvt_pk_bf16_f32 v97, v50, v51
	ds_write_b16 v90, v97 offset:288
	ds_write_b16_d16_hi v90, v97 offset:432
	v_cvt_pk_bf16_f32 v98, v52, v53
	ds_write_b16 v90, v98 offset:1152
	ds_write_b16_d16_hi v90, v98 offset:1296
	v_cvt_pk_bf16_f32 v99, v54, v55
	ds_write_b16 v90, v99 offset:1440
	ds_write_b16_d16_hi v90, v99 offset:1584
	v_cvt_pk_bf16_f32 v100, v56, v57
	ds_write_b16 v90, v100 offset:2304
	ds_write_b16_d16_hi v90, v100 offset:2448
	v_cvt_pk_bf16_f32 v101, v58, v59
	ds_write_b16 v90, v101 offset:2592
	ds_write_b16_d16_hi v90, v101 offset:2736
	v_cvt_pk_bf16_f32 v102, v60, v61
	ds_write_b16 v90, v102 offset:3456
	ds_write_b16_d16_hi v90, v102 offset:3600
	v_cvt_pk_bf16_f32 v103, v62, v63
	ds_write_b16 v90, v103 offset:3744
	ds_write_b16_d16_hi v90, v103 offset:3888
	v_cvt_pk_bf16_f32 v104, v64, v65
	ds_write_b16 v90, v104 offset:64
	ds_write_b16_d16_hi v90, v104 offset:208
	v_cvt_pk_bf16_f32 v105, v66, v67
	ds_write_b16 v90, v105 offset:352
	ds_write_b16_d16_hi v90, v105 offset:496
	v_cvt_pk_bf16_f32 v106, v68, v69
	ds_write_b16 v90, v106 offset:1216
	ds_write_b16_d16_hi v90, v106 offset:1360
	v_cvt_pk_bf16_f32 v107, v70, v71
	ds_write_b16 v90, v107 offset:1504
	ds_write_b16_d16_hi v90, v107 offset:1648
	v_cvt_pk_bf16_f32 v108, v72, v73
	ds_write_b16 v90, v108 offset:2368
	ds_write_b16_d16_hi v90, v108 offset:2512
	v_cvt_pk_bf16_f32 v109, v74, v75
	ds_write_b16 v90, v109 offset:2656
	ds_write_b16_d16_hi v90, v109 offset:2800
	v_cvt_pk_bf16_f32 v110, v76, v77
	ds_write_b16 v90, v110 offset:3520
	ds_write_b16_d16_hi v90, v110 offset:3664
	v_cvt_pk_bf16_f32 v111, v78, v79
	ds_write_b16 v90, v111 offset:3808
	ds_write_b16_d16_hi v90, v111 offset:3952
	v_cvt_pk_bf16_f32 v112, v16, v17
	ds_write_b16 v90, v112 offset:4608
	ds_write_b16_d16_hi v90, v112 offset:4752
	v_cvt_pk_bf16_f32 v113, v18, v19
	ds_write_b16 v90, v113 offset:4896
	ds_write_b16_d16_hi v90, v113 offset:5040
	v_cvt_pk_bf16_f32 v114, v20, v21
	ds_write_b16 v90, v114 offset:5760
	ds_write_b16_d16_hi v90, v114 offset:5904
	v_cvt_pk_bf16_f32 v115, v22, v23
	ds_write_b16 v90, v115 offset:6048
	ds_write_b16_d16_hi v90, v115 offset:6192
	v_cvt_pk_bf16_f32 v116, v24, v25
	ds_write_b16 v90, v116 offset:6912
	ds_write_b16_d16_hi v90, v116 offset:7056
	v_cvt_pk_bf16_f32 v117, v26, v27
	ds_write_b16 v90, v117 offset:7200
	ds_write_b16_d16_hi v90, v117 offset:7344
	v_cvt_pk_bf16_f32 v118, v28, v29
	ds_write_b16 v90, v118 offset:8064
	ds_write_b16_d16_hi v90, v118 offset:8208
	v_cvt_pk_bf16_f32 v119, v30, v31
	ds_write_b16 v90, v119 offset:8352
	ds_write_b16_d16_hi v90, v119 offset:8496
	v_cvt_pk_bf16_f32 v120, v32, v33
	ds_write_b16 v90, v120 offset:4672
	ds_write_b16_d16_hi v90, v120 offset:4816
	v_cvt_pk_bf16_f32 v121, v34, v35
	ds_write_b16 v90, v121 offset:4960
	ds_write_b16_d16_hi v90, v121 offset:5104
	v_cvt_pk_bf16_f32 v122, v36, v37
	ds_write_b16 v90, v122 offset:5824
	ds_write_b16_d16_hi v90, v122 offset:5968
	v_cvt_pk_bf16_f32 v123, v38, v39
	ds_write_b16 v90, v123 offset:6112
	ds_write_b16_d16_hi v90, v123 offset:6256
	v_cvt_pk_bf16_f32 v124, v40, v41
	ds_write_b16 v90, v124 offset:6976
	ds_write_b16_d16_hi v90, v124 offset:7120
	v_cvt_pk_bf16_f32 v125, v42, v43
	ds_write_b16 v90, v125 offset:7264
	ds_write_b16_d16_hi v90, v125 offset:7408
	v_cvt_pk_bf16_f32 v126, v44, v45
	ds_write_b16 v90, v126 offset:8128
	ds_write_b16_d16_hi v90, v126 offset:8272
	v_cvt_pk_bf16_f32 v127, v46, v47
	ds_write_b16 v90, v127 offset:8416
	ds_write_b16_d16_hi v90, v127 offset:8560
	s_waitcnt lgkmcnt(0)
	ds_read_b128 v[96:99], v94
	ds_read_b128 v[100:103], v94 offset:1152
	ds_read_b128 v[104:107], v94 offset:2304
	ds_read_b128 v[108:111], v94 offset:3456
	ds_read_b128 v[112:115], v94 offset:4608
	ds_read_b128 v[116:119], v94 offset:5760
	ds_read_b128 v[120:123], v94 offset:6912
	ds_read_b128 v[124:127], v94 offset:8064
	s_waitcnt lgkmcnt(7)
	global_store_dwordx4 v95, v[96:99], s[32:33]
	s_add_u32 s32, s32, 1536
	s_addc_u32 s33, s33, 0
	s_waitcnt lgkmcnt(6)
	global_store_dwordx4 v95, v[100:103], s[32:33]
	s_add_u32 s32, s32, 1536
	s_addc_u32 s33, s33, 0
	s_waitcnt lgkmcnt(5)
	global_store_dwordx4 v95, v[104:107], s[32:33]
	s_add_u32 s32, s32, 1536
	s_addc_u32 s33, s33, 0
	s_waitcnt lgkmcnt(4)
	global_store_dwordx4 v95, v[108:111], s[32:33]
	s_add_u32 s32, s32, 1536
	s_addc_u32 s33, s33, 0
	s_waitcnt lgkmcnt(3)
	global_store_dwordx4 v95, v[112:115], s[32:33]
	s_add_u32 s32, s32, 1536
	s_addc_u32 s33, s33, 0
	s_waitcnt lgkmcnt(2)
	global_store_dwordx4 v95, v[116:119], s[32:33]
	s_add_u32 s32, s32, 1536
	s_addc_u32 s33, s33, 0
	s_waitcnt lgkmcnt(1)
	global_store_dwordx4 v95, v[120:123], s[32:33]
	s_add_u32 s32, s32, 1536
	s_addc_u32 s33, s33, 0
	s_waitcnt lgkmcnt(0)
	global_store_dwordx4 v95, v[124:127], s[32:33]
	s_mov_b64 s[6:7], -1
	s_movk_i32 s34, 0x3fff
	s_branch .LBB0_1708
.Lp4kv_orig:
	s_cbranch_vccz .LBB0_1678
	v_lshlrev_b32_e32 v160, 1, v86
	s_nop 2
	v_cvt_pk_bf16_f32 v88, v48, v49
	v_cvt_pk_bf16_f32 v89, v50, v51
	v_lshl_add_u64 v[92:93], v[82:83], 0, v[160:161]
	s_nop 1
	v_cvt_pk_bf16_f32 v90, v64, v65
	v_cvt_pk_bf16_f32 v91, v66, v67
	global_store_dwordx2 v[92:93], v[88:89], off
	v_lshl_add_u64 v[88:89], v[80:81], 0, v[160:161]
	global_store_dwordx2 v[88:89], v[90:91], off
	s_mov_b64 s[0:1], 0
